# scan stage 1 rewritten: both key tiles together, batched LDS reads, no per-element branch ladders; SSD staging via ds_bpermute
# baseline (speedup 1.0000x reference)
.LBB0_561:
	s_andn2_b64 vcc, exec, s[12:13]
	v_and_b32_e32 v111, 63, v113
	s_cbranch_vccnz .LBB0_565
	v_add_f32_e32 v16, v125, v88
	v_mul_f32_e32 v17, 0x3fb8aa3b, v16
	v_exp_f32_e32 v17, v17
	v_mov_b32_e32 v19, 0
	v_ashrrev_i32_e32 v63, 4, v113
	v_lshlrev_b32_e32 v58, 16, v27
	v_add_f32_e32 v17, 1.0, v17
	v_cmp_gt_f32_e32 vcc, s56, v17
	v_and_b32_e32 v59, 0xffff0000, v27
	s_nop 0
	v_cndmask_b32_e64 v18, 0, 32, vcc
	v_ldexp_f32 v17, v17, v18
	v_log_f32_e32 v17, v17
	v_cndmask_b32_e32 v20, 0, v123, vcc
	v_mov_b32_e32 v18, 0
	v_mul_f32_e32 v22, 0x3f317217, v17
	v_fma_f32 v22, v17, s57, -v22
	v_fmac_f32_e32 v22, 0x3377d1cf, v17
	v_fmac_f32_e32 v22, 0x3f317217, v17
	v_cmp_lt_f32_e64 vcc, |v17|, s58
	s_nop 1
	v_cndmask_b32_e32 v17, v17, v22, vcc
	v_sub_f32_e32 v17, v17, v20
	v_cmp_lt_f32_e32 vcc, s55, v16
	s_nop 1
	v_cndmask_b32_e32 v16, v17, v16, vcc
	v_mul_f32_e32 v17, v126, v16
	v_cmp_lt_i32_e32 vcc, s65, v113
	s_nop 0
	v_mov_b32_dpp v17, v17 row_shr:1 row_mask:0xf bank_mask:0xf bound_ctrl:1
	v_fmac_f32_e32 v17, v126, v16
	s_nop 1
	v_add_f32_dpp v17, v17, v17 row_shr:2 row_mask:0xf bank_mask:0xf bound_ctrl:1
	s_nop 1
	v_add_f32_dpp v17, v17, v17 row_shr:4 row_mask:0xf bank_mask:0xf bound_ctrl:1
	s_nop 1
	v_add_f32_dpp v17, v17, v17 row_shr:8 row_mask:0xf bank_mask:0xf bound_ctrl:1
	s_nop 1
	v_mov_b32_dpp v18, v17 row_bcast:15 row_mask:0xa bank_mask:0xf bound_ctrl:1
	v_add_f32_e32 v17, v17, v18
	s_nop 1
	v_mov_b32_dpp v19, v17 row_bcast:31 row_mask:0xc bank_mask:0xf bound_ctrl:1
	v_add_f32_e32 v60, v17, v19
	v_lshl_add_u32 v17, v111, 2, s71
	ds_write2st64_b32 v17, v16, v60 offset1:1
	v_ashrrev_i32_e32 v150, 3, v113
	v_lshlrev_b32_e32 v150, 2, v150
	v_lshlrev_b32_e32 v151, 2, v63
	v_add_u32_e32 v152, 0x80, v151
	ds_bpermute_b32 v20, v150, v16
	ds_bpermute_b32 v154, v151, v60
	ds_bpermute_b32 v155, v152, v60
	v_ashrrev_i32_e32 v17, 3, v113
	v_lshlrev_b32_e32 v16, 4, v113
	v_mul_lo_u32 v61, v17, s54
	v_and_b32_e32 v62, 0x70, v16
	v_add3_u32 v18, s59, v61, v62
	v_and_b32_e32 v16, 0xf0, v16
	ds_write_b128 v18, v[92:95]
	v_add3_u32 v18, s64, v61, v62
	v_add_u32_e32 v16, 0, v16
	ds_write_b128 v18, v[24:27]
	v_mad_u64_u32 v[22:23], s[12:13], v63, s53, v[16:17]
	v_add_u32_e32 v18, 0x200, v113
	v_ashrrev_i32_e32 v23, 4, v18
	v_mad_u64_u32 v[56:57], s[12:13], v23, s53, v[16:17]
	ds_write_b128 v22, v[28:31] offset:17408
	ds_write_b128 v22, v[36:39]
	ds_write_b128 v56, v[32:35] offset:17408
	ds_write_b128 v56, v[40:43]
	v_lshlrev_b32_e32 v16, 16, v24
	v_and_b32_e32 v17, 0xffff0000, v24
	v_lshlrev_b32_e32 v18, 16, v25
	v_and_b32_e32 v19, 0xffff0000, v25
	s_waitcnt lgkmcnt(6)
	v_pk_mul_f32 v[16:17], v[20:21], v[16:17] op_sel_hi:[0,1]
	v_pk_mul_f32 v[18:19], v[20:21], v[18:19] op_sel_hi:[0,1]
	v_cvt_pk_bf16_f32 v16, v16, v17
	v_cvt_pk_bf16_f32 v17, v18, v19
	v_lshlrev_b32_e32 v18, 16, v26
	v_and_b32_e32 v19, 0xffff0000, v26
	v_pk_mul_f32 v[18:19], v[20:21], v[18:19] op_sel_hi:[0,1]
	v_pk_mul_f32 v[58:59], v[20:21], v[58:59] op_sel_hi:[0,1]
	v_cvt_pk_bf16_f32 v18, v18, v19
	v_cvt_pk_bf16_f32 v19, v58, v59
	v_add3_u32 v20, 0, v61, v62
	ds_write_b128 v20, v[16:19] offset:52224
	v_readlane_b32 s16, v60, 63
	v_and_b32_e32 v17, 0xffff0000, v28
	v_lshlrev_b32_e32 v18, 16, v29
	v_and_b32_e32 v19, 0xffff0000, v29
	v_sub_f32_e32 v16, s16, v154
	v_mul_f32_e32 v16, 0x3fb8aa3b, v16
	v_exp_f32_e32 v20, v16
	v_lshlrev_b32_e32 v16, 16, v28
	v_lshlrev_b32_e32 v58, 16, v31
	v_and_b32_e32 v59, 0xffff0000, v31
	v_pk_mul_f32 v[16:17], v[20:21], v[16:17] op_sel_hi:[0,1]
	v_pk_mul_f32 v[18:19], v[20:21], v[18:19] op_sel_hi:[0,1]
	v_cvt_pk_bf16_f32 v16, v16, v17
	v_cvt_pk_bf16_f32 v17, v18, v19
	v_lshlrev_b32_e32 v18, 16, v30
	v_and_b32_e32 v19, 0xffff0000, v30
	v_pk_mul_f32 v[18:19], v[20:21], v[18:19] op_sel_hi:[0,1]
	v_pk_mul_f32 v[58:59], v[20:21], v[58:59] op_sel_hi:[0,1]
	v_cvt_pk_bf16_f32 v18, v18, v19
	v_cvt_pk_bf16_f32 v19, v58, v59
	ds_write_b128 v22, v[16:19] offset:34816
	v_and_b32_e32 v17, 0xffff0000, v32
	v_lshlrev_b32_e32 v18, 16, v33
	v_and_b32_e32 v19, 0xffff0000, v33
	v_lshlrev_b32_e32 v22, 16, v35
	v_sub_f32_e32 v16, s16, v155
	v_mul_f32_e32 v16, 0x3fb8aa3b, v16
	v_exp_f32_e32 v20, v16
	v_lshlrev_b32_e32 v16, 16, v32
	v_and_b32_e32 v23, 0xffff0000, v35
	v_pk_mul_f32 v[16:17], v[20:21], v[16:17] op_sel_hi:[0,1]
	v_pk_mul_f32 v[18:19], v[20:21], v[18:19] op_sel_hi:[0,1]
	v_cvt_pk_bf16_f32 v16, v16, v17
	v_cvt_pk_bf16_f32 v17, v18, v19
	v_lshlrev_b32_e32 v18, 16, v34
	v_and_b32_e32 v19, 0xffff0000, v34
	v_pk_mul_f32 v[18:19], v[20:21], v[18:19] op_sel_hi:[0,1]
	v_pk_mul_f32 v[22:23], v[20:21], v[22:23] op_sel_hi:[0,1]
	v_cvt_pk_bf16_f32 v18, v18, v19
	v_cvt_pk_bf16_f32 v19, v22, v23
	ds_write_b128 v56, v[16:19] offset:34816
	s_and_saveexec_b64 s[12:13], vcc
	s_cbranch_execz .LBB0_564
	v_mul_f32_e32 v16, s16, v124
	v_exp_f32_e32 v16, v16
	s_add_i32 s16, 0, 0x19800
	v_lshl_add_u32 v17, v113, 2, s16
	v_add_u32_e32 v17, 0xfffffa00, v17
	ds_write_b32 v17, v16

.LBB0_574:
	s_and_b64 vcc, exec, s[12:13]
	s_cbranch_vccz .LBB0_556
	v_and_b32_e32 v107, 15, v113
	v_and_b32_e32 v133, 48, v113
	v_or_b32_e32 v132, s72, v107
	v_add_u32_e32 v20, 0, v133
	v_mad_u64_u32 v[22:23], s[12:13], v132, s53, v[20:21]
	v_lshrrev_b32_e32 v60, 4, v111
	v_lshlrev_b32_e32 v109, 2, v60
	v_or_b32_e32 v127, s72, v109
	v_or_b32_e32 v61, s77, v107
	v_or_b32_e32 v62, s78, v107
	s_and_b64 vcc, exec, s[8:9]
	s_cbranch_vccnz .Ls1_noacum
	v_lshl_add_u32 v150, v127, 2, s71
	v_lshl_add_u32 v151, v61, 2, s71
	v_lshl_add_u32 v152, v62, 2, s71
	ds_read_b128 v[168:171], v150 offset:256
	ds_read_b32 v172, v151 offset:256
	ds_read_b32 v173, v152 offset:256
.Ls1_noacum:
	ds_read_b128 v[16:19], v22
	ds_read_b128 v[80:83], v22 offset:64
	ds_read_b128 v[84:87], v22 offset:128
	ds_read_b128 v[96:99], v22 offset:192
	s_andn2_b64 vcc, exec, s[46:47]
	s_cbranch_vccnz .Ls1_none
	v_mad_u32_u24 v23, v61, s53, v20
	ds_read_b128 v[154:157], v23 offset:17408
	ds_read_b128 v[158:161], v23 offset:17472
	ds_read_b128 v[162:165], v23 offset:17536
	ds_read_b128 v[176:179], v23 offset:17600
	s_andn2_b64 vcc, exec, s[48:49]
	s_cbranch_vccnz .Ls1_only0
	v_mad_u32_u24 v153, v62, s53, v20
	ds_read_b128 v[68:71], v153 offset:17408
	ds_read_b128 v[72:75], v153 offset:17472
	ds_read_b128 v[76:79], v153 offset:17536
	ds_read_b128 v[100:103], v153 offset:17600
	s_waitcnt lgkmcnt(7)
	v_mfma_f32_16x16x32_bf16 v[56:59], v[16:19], v[154:157], 0
	s_waitcnt lgkmcnt(3)
	v_mfma_f32_16x16x32_bf16 v[64:67], v[16:19], v[68:71], 0
	v_mfma_f32_16x16x32_bf16 v[56:59], v[80:83], v[158:161], v[56:59]
	s_waitcnt lgkmcnt(2)
	v_mfma_f32_16x16x32_bf16 v[64:67], v[80:83], v[72:75], v[64:67]
	v_mfma_f32_16x16x32_bf16 v[56:59], v[84:87], v[162:165], v[56:59]
	s_waitcnt lgkmcnt(1)
	v_mfma_f32_16x16x32_bf16 v[64:67], v[84:87], v[76:79], v[64:67]
	v_mfma_f32_16x16x32_bf16 v[56:59], v[96:99], v[176:179], v[56:59]
	s_waitcnt lgkmcnt(0)
	v_mfma_f32_16x16x32_bf16 v[64:67], v[96:99], v[100:103], v[64:67]
	s_branch .Ls1_mdone
.Ls1_only0:
	v_mov_b32_e32 v64, 0
	v_mov_b32_e32 v65, 0
	v_mov_b32_e32 v66, 0
	v_mov_b32_e32 v67, 0
	s_waitcnt lgkmcnt(3)
	v_mfma_f32_16x16x32_bf16 v[56:59], v[16:19], v[154:157], 0
	s_waitcnt lgkmcnt(2)
	v_mfma_f32_16x16x32_bf16 v[56:59], v[80:83], v[158:161], v[56:59]
	s_waitcnt lgkmcnt(1)
	v_mfma_f32_16x16x32_bf16 v[56:59], v[84:87], v[162:165], v[56:59]
	s_waitcnt lgkmcnt(0)
	v_mfma_f32_16x16x32_bf16 v[56:59], v[96:99], v[176:179], v[56:59]
	s_branch .Ls1_mdone
.Ls1_none:
	v_mov_b32_e32 v56, 0
	v_mov_b32_e32 v57, 0
	v_mov_b32_e32 v58, 0
	v_mov_b32_e32 v59, 0
	v_mov_b32_e32 v64, 0
	v_mov_b32_e32 v65, 0
	v_mov_b32_e32 v66, 0
	v_mov_b32_e32 v67, 0
.Ls1_mdone:
	v_or_b32_e32 v131, 1, v127
	v_or_b32_e32 v129, 2, v127
	v_or_b32_e32 v23, 3, v127
	v_cmp_le_u32_e64 s[12:13], v61, v127
	v_cmp_le_u32_e64 s[88:89], v61, v131
	v_cmp_le_u32_e64 s[90:91], v61, v129
	v_cmp_le_u32_e64 s[92:93], v61, v23
	v_cmp_le_u32_e64 s[94:95], v62, v127
	v_cmp_le_u32_e64 s[96:97], v62, v131
	v_cmp_le_u32_e64 s[98:99], v62, v129
	v_cmp_le_u32_e64 s[100:101], v62, v23
	v_lshlrev_b32_e32 v112, 1, v61
	v_mul_lo_u32 v128, v127, s54
	v_lshlrev_b32_e32 v22, 1, v62
	v_cndmask_b32_e64 v56, 0, v56, s[12:13]
	v_cndmask_b32_e64 v57, 0, v57, s[88:89]
	v_cndmask_b32_e64 v58, 0, v58, s[90:91]
	v_cndmask_b32_e64 v59, 0, v59, s[92:93]
	v_cndmask_b32_e64 v64, 0, v64, s[94:95]
	v_cndmask_b32_e64 v65, 0, v65, s[96:97]
	v_cndmask_b32_e64 v66, 0, v66, s[98:99]
	v_cndmask_b32_e64 v67, 0, v67, s[100:101]
	v_add_u32_e32 v150, v112, v128
	v_add_u32_e32 v151, v22, v128
	s_and_b64 vcc, exec, s[8:9]
	s_cbranch_vccnz .Ls1_write
	s_waitcnt lgkmcnt(0)
	v_sub_f32_e32 v180, v168, v172
	v_sub_f32_e32 v181, v169, v172
	v_sub_f32_e32 v182, v170, v172
	v_sub_f32_e32 v183, v171, v172
	v_sub_f32_e32 v184, v168, v173
	v_sub_f32_e32 v185, v169, v173
	v_sub_f32_e32 v186, v170, v173
	v_sub_f32_e32 v187, v171, v173
	v_min_f32_e32 v180, 0, v180
	v_min_f32_e32 v181, 0, v181
	v_min_f32_e32 v182, 0, v182
	v_min_f32_e32 v183, 0, v183
	v_min_f32_e32 v184, 0, v184
	v_min_f32_e32 v185, 0, v185
	v_min_f32_e32 v186, 0, v186
	v_min_f32_e32 v187, 0, v187
	v_mul_f32_e32 v180, 0x3fb8aa3b, v180
	v_mul_f32_e32 v181, 0x3fb8aa3b, v181
	v_mul_f32_e32 v182, 0x3fb8aa3b, v182
	v_mul_f32_e32 v183, 0x3fb8aa3b, v183
	v_mul_f32_e32 v184, 0x3fb8aa3b, v184
	v_mul_f32_e32 v185, 0x3fb8aa3b, v185
	v_mul_f32_e32 v186, 0x3fb8aa3b, v186
	v_mul_f32_e32 v187, 0x3fb8aa3b, v187
	v_exp_f32_e32 v180, v180
	v_exp_f32_e32 v181, v181
	v_exp_f32_e32 v182, v182
	v_exp_f32_e32 v183, v183
	v_exp_f32_e32 v184, v184
	v_exp_f32_e32 v185, v185
	v_exp_f32_e32 v186, v186
	v_exp_f32_e32 v187, v187
	v_mul_f32_e32 v56, v56, v180
	v_mul_f32_e32 v57, v57, v181
	v_mul_f32_e32 v58, v58, v182
	v_mul_f32_e32 v59, v59, v183
	v_mul_f32_e32 v64, v64, v184
	v_mul_f32_e32 v65, v65, v185
	v_mul_f32_e32 v66, v66, v186
	v_mul_f32_e32 v67, v67, v187
.Ls1_write:
	v_cvt_pk_bf16_f32 v56, v56, s0
	v_cvt_pk_bf16_f32 v57, v57, s0
	v_cvt_pk_bf16_f32 v58, v58, s0
	v_cvt_pk_bf16_f32 v59, v59, s0
	v_cvt_pk_bf16_f32 v64, v64, s0
	v_cvt_pk_bf16_f32 v65, v65, s0
	v_cvt_pk_bf16_f32 v66, v66, s0
	v_cvt_pk_bf16_f32 v67, v67, s0
	ds_write_b16 v150, v56 offset:61440
	ds_write_b16 v150, v57 offset:61584
	ds_write_b16 v150, v58 offset:61728
	ds_write_b16 v150, v59 offset:61872
	ds_write_b16 v151, v64 offset:61440
	ds_write_b16 v151, v65 offset:61584
	ds_write_b16 v151, v66 offset:61728
	ds_write_b16 v151, v67 offset:61872
	v_lshrrev_b32_e32 v57, 2, v107
	v_lshlrev_b32_e32 v20, 3, v113
	v_lshl_or_b32 v60, v60, 3, v57
	v_add_u32_e32 v56, s73, v133
	s_waitcnt lgkmcnt(4)
	v_and_b32_e32 v61, 24, v20
	v_mul_u32_u24_e32 v57, 0x110, v60
	v_add3_u32 v114, s81, v61, v57
	ds_read_b128 v[56:59], v56
	v_mad_u32_u24 v130, v60, s54, v61
	v_add_u32_e32 v115, s66, v130
	ds_read_b64_tr_b16 v[146:147], v114 offset:0
	ds_read_b64_tr_b16 v[148:149], v114 offset:1088
	ds_read_b64_tr_b16 v[142:143], v114 offset:8704
	ds_read_b64_tr_b16 v[144:145], v114 offset:9792
	ds_read_b64_tr_b16 v[138:139], v115 offset:0
	ds_read_b64_tr_b16 v[140:141], v115 offset:576
	ds_read_b64_tr_b16 v[134:135], v115 offset:4608
	ds_read_b64_tr_b16 v[136:137], v115 offset:5184
	ds_read_b64_tr_b16 v[100:101], v115 offset:32
	ds_read_b64_tr_b16 v[102:103], v115 offset:608
	ds_read_b64_tr_b16 v[76:77], v115 offset:4640
	ds_read_b64_tr_b16 v[78:79], v115 offset:5216
	ds_read_b64_tr_b16 v[72:73], v115 offset:64
	ds_read_b64_tr_b16 v[74:75], v115 offset:640
	ds_read_b64_tr_b16 v[68:69], v115 offset:4672
	ds_read_b64_tr_b16 v[70:71], v115 offset:5248
	ds_read_b64_tr_b16 v[64:65], v115 offset:96
	ds_read_b64_tr_b16 v[66:67], v115 offset:672
	ds_read_b64_tr_b16 v[60:61], v115 offset:4704
	ds_read_b64_tr_b16 v[62:63], v115 offset:5280
	s_waitcnt lgkmcnt(0)
	s_cmp_eq_u32 s83, 63
	s_waitcnt lgkmcnt(0)
	v_pk_mul_f32 v[2:3], v[2:3], v[58:59]
	v_pk_mul_f32 v[0:1], v[0:1], v[56:57]
	v_pk_mul_f32 v[6:7], v[6:7], v[58:59]
	v_pk_mul_f32 v[4:5], v[4:5], v[56:57]
	v_pk_mul_f32 v[10:11], v[10:11], v[58:59]
	v_pk_mul_f32 v[8:9], v[8:9], v[56:57]
	v_pk_mul_f32 v[14:15], v[14:15], v[58:59]
	v_pk_mul_f32 v[12:13], v[12:13], v[56:57]
	v_mfma_f32_16x16x32_bf16 v[0:3], v[146:149], v[138:141], v[0:3]
	v_mfma_f32_16x16x32_bf16 v[4:7], v[146:149], v[100:103], v[4:7]
	v_mfma_f32_16x16x32_bf16 v[8:11], v[146:149], v[72:75], v[8:11]
	v_mfma_f32_16x16x32_bf16 v[12:15], v[146:149], v[64:67], v[12:15]
	v_mfma_f32_16x16x32_bf16 v[0:3], v[142:145], v[134:137], v[0:3]
	v_mfma_f32_16x16x32_bf16 v[4:7], v[142:145], v[76:79], v[4:7]
	v_mfma_f32_16x16x32_bf16 v[8:11], v[142:145], v[68:71], v[8:11]
	v_mfma_f32_16x16x32_bf16 v[12:15], v[142:145], v[60:63], v[12:15]
	s_cbranch_scc1 .LBB0_605
	s_add_i32 s50, s69, 64
	v_and_b32_e32 v24, 0x78, v20
	v_ashrrev_i32_e32 v25, 4, v113
	v_add_u32_e32 v26, 0x200, v113
	v_ashrrev_i32_e32 v27, 3, v113
	v_and_b32_e32 v28, 56, v20
	s_mov_b64 s[12:13], -1
	s_and_b64 vcc, exec, s[10:11]
	v_lshlrev_b32_e32 v20, 1, v24
	v_add_u32_e32 v24, s50, v25
	v_ashrrev_i32_e32 v32, 4, v26
	v_add_u32_e32 v26, s50, v27
	v_lshlrev_b32_e32 v114, 1, v28
	s_cbranch_vccnz .LBB0_602
	v_mov_b32_e32 v56, v24
	v_mov_b32_e32 v58, v26
	v_add_u32_e32 v62, s50, v32
	v_lshl_add_u64 v[60:61], s[36:37], 0, v[20:21]
	v_ashrrev_i32_e32 v57, 31, v56
	v_mad_i64_i32 v[64:65], s[12:13], v56, s3, v[60:61]
	v_lshl_add_u64 v[66:67], s[38:39], 0, v[20:21]
	global_load_dwordx4 v[24:27], v[64:65], off
	global_load_dwordx4 v[32:35], v[64:65], off offset:1024
	v_lshlrev_b64 v[64:65], 10, v[56:57]
	v_lshl_add_u64 v[64:65], v[66:67], 0, v[64:65]
	global_load_dwordx4 v[40:43], v[64:65], off
	v_ashrrev_i32_e32 v63, 31, v62
	v_mad_i64_i32 v[60:61], s[12:13], v62, s3, v[60:61]
	global_load_dwordx4 v[28:31], v[60:61], off
	global_load_dwordx4 v[36:39], v[60:61], off offset:1024
	v_lshlrev_b64 v[60:61], 10, v[62:63]
	v_lshl_add_u64 v[60:61], v[66:67], 0, v[60:61]
	global_load_dwordx4 v[44:47], v[60:61], off
	v_mov_b64_e32 v[60:61], s[40:41]
	v_mad_i64_i32 v[60:61], s[12:13], v58, s3, v[60:61]
	v_mov_b32_e32 v115, v21
	v_lshl_add_u64 v[60:61], v[60:61], 0, v[114:115]
	global_load_dwordx4 v[92:95], v[60:61], off
	v_cmp_gt_i32_e32 vcc, 32, v113
	s_and_saveexec_b64 s[12:13], vcc
	s_cbranch_execz .LBB0_601
	s_add_i32 s86, s82, s83
	s_ashr_i32 s87, s86, 31
	s_lshl_b64 s[86:87], s[86:87], 11
	s_add_u32 s86, s74, s86
	v_lshlrev_b32_e32 v60, 2, v113
	s_addc_u32 s87, s75, s87
	v_ashrrev_i32_e32 v61, 31, v60
	v_lshl_add_u64 v[60:61], v[60:61], 2, s[86:87]
	global_load_dwordx4 v[88:91], v[60:61], off

.Lscan_eA_ssd:
	v_add_u32_e32 v154, s59, v112
	v_add_u32_e32 v155, s64, v112
	v_add_u32_e32 v154, v154, v128
	v_add_u32_e32 v155, v155, v128
	ds_read_u16 v160, v154
	ds_read_u16 v161, v154 offset:144
	ds_read_u16 v162, v154 offset:288
	ds_read_u16 v163, v154 offset:432
	ds_read_u16 v164, v155
	ds_read_u16 v165, v155 offset:144
	ds_read_u16 v166, v155 offset:288
	ds_read_u16 v167, v155 offset:432
	s_lshl_b64 s[12:13], s[34:35], 1
	s_add_u32 s12, s28, s12
	s_addc_u32 s13, s29, s13
	v_mov_b32_e32 v198, v112
	v_mov_b32_e32 v199, 0
	v_lshl_add_u64 v[198:199], s[12:13], 0, v[198:199]
	v_add_u32_e32 v150, s84, v127
	v_add_u32_e32 v151, s84, v131
	v_add_u32_e32 v152, s84, v129
	v_add_u32_e32 v153, s84, v23
	v_mov_b32_e32 v184, v110
	v_mov_b32_e32 v186, v110
	v_mov_b32_e32 v188, v110
	v_mov_b32_e32 v190, v110
	s_waitcnt lgkmcnt(0)
	v_mul_f32_e32 v168, 0x3fb8aa3b, v168
	v_mul_f32_e32 v169, 0x3fb8aa3b, v169
	v_mul_f32_e32 v170, 0x3fb8aa3b, v170
	v_mul_f32_e32 v171, 0x3fb8aa3b, v171
	v_exp_f32_e32 v172, v168
	v_exp_f32_e32 v173, v169
	v_exp_f32_e32 v174, v170
	v_exp_f32_e32 v175, v171
	v_lshlrev_b32_e32 v177, 16, v160
	v_lshlrev_b32_e32 v179, 16, v161
	v_lshlrev_b32_e32 v181, 16, v162
	v_lshlrev_b32_e32 v183, 16, v163
	v_mul_f32_e32 v160, 0xbfb8aa3b, v177
	v_mul_f32_e32 v161, 0xbfb8aa3b, v179
	v_mul_f32_e32 v162, 0xbfb8aa3b, v181
	v_mul_f32_e32 v163, 0xbfb8aa3b, v183
	v_exp_f32_e32 v160, v160
	v_exp_f32_e32 v161, v161
	v_exp_f32_e32 v162, v162
	v_exp_f32_e32 v163, v163
	v_lshlrev_b32_e32 v176, 16, v164
	v_lshlrev_b32_e32 v178, 16, v165
	v_lshlrev_b32_e32 v180, 16, v166
	v_lshlrev_b32_e32 v182, 16, v167
	v_add_f32_e32 v160, 1.0, v160
	v_add_f32_e32 v161, 1.0, v161
	v_add_f32_e32 v162, 1.0, v162
	v_add_f32_e32 v163, 1.0, v163
	v_rcp_f32_e32 v185, v160
	v_rcp_f32_e32 v187, v161
	v_rcp_f32_e32 v189, v162
	v_rcp_f32_e32 v191, v163
	v_fma_f32 v164, v64, v172, v68
	v_fma_f32 v165, v65, v173, v69
	v_fma_f32 v166, v66, v174, v70
	v_fma_f32 v167, v67, v175, v71
	v_pk_mul_f32 v[176:177], v[184:185], v[176:177]
	v_pk_mul_f32 v[178:179], v[186:187], v[178:179]
	v_pk_mul_f32 v[180:181], v[188:189], v[180:181]
	v_pk_mul_f32 v[182:183], v[190:191], v[182:183]
	v_add_f32_e32 v164, v176, v164
	v_add_f32_e32 v165, v178, v165
	v_add_f32_e32 v166, v180, v166
	v_add_f32_e32 v167, v182, v167
	v_mul_f32_e32 v164, v164, v177
	v_mul_f32_e32 v165, v165, v179
	v_mul_f32_e32 v166, v166, v181
	v_mul_f32_e32 v167, v167, v183
	v_mad_i64_i32 v[194:195], s[92:93], v150, s3, v[198:199]
	v_cvt_pk_bf16_f32 v196, v164, s0
	global_store_short v[194:195], v196, off
	v_mad_i64_i32 v[194:195], s[92:93], v151, s3, v[198:199]
	v_cvt_pk_bf16_f32 v196, v165, s0
	global_store_short v[194:195], v196, off
	v_mad_i64_i32 v[194:195], s[92:93], v152, s3, v[198:199]
	v_cvt_pk_bf16_f32 v196, v166, s0
	global_store_short v[194:195], v196, off
	v_mad_i64_i32 v[194:195], s[92:93], v153, s3, v[198:199]
	v_cvt_pk_bf16_f32 v196, v167, s0
	global_store_short v[194:195], v196, off
	s_branch .LBB0_647

.LBB0_611:
	s_mov_b64 s[50:51], s[34:35]
	s_and_b64 vcc, exec, s[12:13]
	v_add_u32_e32 v20, s84, v127
	s_cbranch_vccnz .LBB0_616
	s_branch .LBB0_617
.LBB0_614:
	s_mov_b64 s[12:13], 0
	v_add_u32_e32 v72, s64, v112
	v_add_u32_e32 v73, s59, v112
	s_cbranch_execnz .LBB0_609
